# attention output stores (diff, neighbourhood, GQA): v_permlane32_swap pairs + 16-byte stores instead of 8-byte row-per-lane stores
# speedup vs baseline: 1.0148x; 1.0030x over previous
; DI float xhalf(float v) { return __shfl_xor(v, 32); }
; template <int NCH, int MODE, bool BOUND> ...
;     ...
;   l += xhalf(l);
;   const float inv = 1.f / l;
; #pragma unroll
;   for (int i = 0; i < 16; ++i) { o0[i] *= inv; o1[i] *= inv; }
; DI void store_o(bf16_t* dst  , const f32x16& o0, const f32x16& o1, int h) {
; #pragma unroll
;   for (int g = 0; g < 4; ++g) {
;     uint2 u;
;     u.x = pk_bf16(o0[4 * g], o0[4 * g + 1]); u.y = pk_bf16(o0[4 * g + 2], o0[4 * g + 3]);
;     *(uint2*)(dst + 8 * g + 4 * h) = u;
;     u.x = pk_bf16(o1[4 * g], o1[4 * g + 1]); u.y = pk_bf16(o1[4 * g + 2], o1[4 * g + 3]);
;     *(uint2*)(dst + 32 + 8 * g + 4 * h) = u;
;   }
; }
.LBB0_127:
	s_waitcnt lgkmcnt(0)
	v_add_f32_e32 v0, v123, v0
	s_waitcnt vmcnt(3)
	v_div_scale_f32 v2, s[0:1], v0, v0, 1.0
	v_rcp_f32_e32 v3, v2
	v_div_scale_f32 v4, vcc, 1.0, v0, 1.0
	s_lshl_b32 s34, s30, 7
	v_fma_f32 v5, -v2, v3, 1.0
	v_fmac_f32_e32 v3, v5, v3
	v_mul_f32_e32 v5, v4, v3
	s_waitcnt vmcnt(2)
	v_fma_f32 v6, -v2, v5, v4
	v_fmac_f32_e32 v5, v6, v3
	v_fma_f32 v2, -v2, v5, v4
	v_div_fmas_f32 v2, v2, v3, v5
	v_div_fixup_f32 v0, v2, v0, 1.0
	v_pk_mul_f32 v[4:5], v[0:1], v[16:17] op_sel_hi:[0,1]
	v_pk_mul_f32 v[2:3], v[32:33], v[0:1] op_sel_hi:[1,0]
	v_pk_mul_f32 v[6:7], v[34:35], v[0:1] op_sel_hi:[1,0]
	v_pk_mul_f32 v[34:35], v[4:5], v[4:5]
	v_pk_mul_f32 v[8:9], v[0:1], v[18:19] op_sel_hi:[0,1]
	v_pk_fma_f32 v[34:35], v[2:3], v[2:3], v[34:35]
	s_waitcnt vmcnt(1)
	v_pk_mul_f32 v[10:11], v[36:37], v[0:1] op_sel_hi:[1,0]
	v_pk_mul_f32 v[12:13], v[0:1], v[20:21] op_sel_hi:[0,1]
	v_pk_mul_f32 v[14:15], v[38:39], v[0:1] op_sel_hi:[1,0]
	v_pk_mul_f32 v[16:17], v[0:1], v[22:23] op_sel_hi:[0,1]
	v_pk_mul_f32 v[18:19], v[40:41], v[0:1] op_sel_hi:[1,0]
	v_pk_mul_f32 v[20:21], v[0:1], v[24:25] op_sel_hi:[0,1]
	v_pk_mul_f32 v[22:23], v[42:43], v[0:1] op_sel_hi:[1,0]
	v_pk_mul_f32 v[24:25], v[0:1], v[26:27] op_sel_hi:[0,1]
	v_pk_mul_f32 v[26:27], v[44:45], v[0:1] op_sel_hi:[1,0]
	v_pk_mul_f32 v[28:29], v[0:1], v[28:29] op_sel_hi:[0,1]
	v_pk_mul_f32 v[32:33], v[46:47], v[0:1] op_sel_hi:[1,0]
	v_pk_mul_f32 v[30:31], v[0:1], v[30:31] op_sel_hi:[0,1]
	v_add_f32_e32 v0, v179, v34
	v_add_f32_e32 v0, v35, v0
	v_pk_mul_f32 v[34:35], v[8:9], v[8:9]
	v_cvt_pk_bf16_f32 v2, v2, v3
	v_pk_fma_f32 v[34:35], v[6:7], v[6:7], v[34:35]
	v_cvt_pk_bf16_f32 v3, v6, v7
	v_add_f32_e32 v0, v34, v0
	v_add_f32_e32 v0, v35, v0
	v_pk_mul_f32 v[34:35], v[12:13], v[12:13]
	s_add_i32 s30, s30, 1
	v_pk_fma_f32 v[34:35], v[10:11], v[10:11], v[34:35]
	s_mov_b64 s[0:1], 0x800000
	v_add_f32_e32 v0, v34, v0
	v_add_f32_e32 v0, v35, v0
	v_pk_mul_f32 v[34:35], v[16:17], v[16:17]
	v_add_u32_e32 v144, 0x744, v144
	v_pk_fma_f32 v[34:35], v[14:15], v[14:15], v[34:35]
	s_cmp_eq_u32 s30, 4
	v_add_f32_e32 v0, v34, v0
	v_add_f32_e32 v0, v35, v0
	v_pk_mul_f32 v[34:35], v[20:21], v[20:21]
	v_lshl_add_u64 v[116:117], v[116:117], 0, s[0:1]
	v_pk_fma_f32 v[34:35], v[18:19], v[18:19], v[34:35]
	s_nop 0
	v_add_f32_e32 v0, v34, v0
	v_add_f32_e32 v0, v35, v0
	v_pk_mul_f32 v[34:35], v[24:25], v[24:25]
	s_nop 0
	v_pk_fma_f32 v[34:35], v[22:23], v[22:23], v[34:35]
	s_nop 0
	v_add_f32_e32 v0, v34, v0
	v_add_f32_e32 v0, v35, v0
	v_pk_mul_f32 v[34:35], v[28:29], v[28:29]
	s_nop 0
	v_pk_fma_f32 v[34:35], v[26:27], v[26:27], v[34:35]
	s_nop 0
	v_add_f32_e32 v0, v34, v0
	v_add_f32_e32 v0, v35, v0
	v_pk_mul_f32 v[34:35], v[30:31], v[30:31]
	s_nop 0
	v_pk_fma_f32 v[34:35], v[32:33], v[32:33], v[34:35]
	s_nop 0
	v_add_f32_e32 v0, v34, v0
	v_add_f32_e32 v179, v35, v0
	v_lshl_add_u64 v[34:35], v[112:113], 0, s[34:35]
	v_cvt_pk_bf16_f32 v6, v4, v5
	v_cvt_pk_bf16_f32 v7, v8, v9
	v_cvt_pk_bf16_f32 v8, v12, v13
	v_cvt_pk_bf16_f32 v9, v16, v17
	v_cvt_pk_bf16_f32 v4, v10, v11
	v_cvt_pk_bf16_f32 v5, v14, v15
	v_cvt_pk_bf16_f32 v10, v18, v19
	v_cvt_pk_bf16_f32 v11, v22, v23
	v_cvt_pk_bf16_f32 v12, v26, v27
	v_cvt_pk_bf16_f32 v13, v32, v33
	v_cvt_pk_bf16_f32 v14, v20, v21
	v_cvt_pk_bf16_f32 v15, v24, v25
	v_cvt_pk_bf16_f32 v16, v28, v29
	v_cvt_pk_bf16_f32 v17, v30, v31
	v_and_b32_e32 v18, 32, v228
	v_lshrrev_b32_e32 v18, 2, v18
	v_mov_b32_e32 v19, 0
	v_lshl_add_u64 v[34:35], v[34:35], 0, v[18:19]
	v_permlane32_swap_b32_e32 v2, v4
	v_permlane32_swap_b32_e32 v3, v5
	v_permlane32_swap_b32_e32 v6, v8
	v_permlane32_swap_b32_e32 v7, v9
	v_permlane32_swap_b32_e32 v10, v12
	v_permlane32_swap_b32_e32 v11, v13
	v_permlane32_swap_b32_e32 v14, v16
	v_permlane32_swap_b32_e32 v15, v17
	global_store_dwordx4 v[34:35], v[2:5], off offset:1536
	global_store_dwordx4 v[34:35], v[10:13], off offset:1568
	global_store_dwordx4 v[34:35], v[6:9], off offset:1600
	global_store_dwordx4 v[34:35], v[14:17], off offset:1632
	s_nop 1
	s_cbranch_scc1 .LBB0_288

; DI int otid() { int t = threadIdx.x; asm volatile("" : "+v"(t)); return t; }
; DI void store_o(bf16_t* dst  , const f32x16& o0, const f32x16& o1, int h) {
; #pragma unroll
;   for (int g = 0; g < 4; ++g) {
;     uint2 u;
;     u.x = pk_bf16(o0[4 * g], o0[4 * g + 1]); u.y = pk_bf16(o0[4 * g + 2], o0[4 * g + 3]);
;     *(uint2*)(dst + 8 * g + 4 * h) = u;
;     u.x = pk_bf16(o1[4 * g], o1[4 * g + 1]); u.y = pk_bf16(o1[4 * g + 2], o1[4 * g + 3]);
;     *(uint2*)(dst + 32 + 8 * g + 4 * h) = u;
;   }
; }
; DI void phase_attn(const Params& p, int layer, char* smem) {
;     ...
; #pragma unroll
;         for (int i = 0; i < 16; ++i) ssq += o0[i] * o0[i] + o1[i] * o1[i] + u0[i] * u0[i] + u1[i] * u1[i];
;         const int tid2 = otid(), qtok2 = b * SEQ + qb * 256 + (tid2 >> 6) * 32 + (tid2 & 31), h2 = (tid2 >> 5) & 1;
;         store_o(ocat + (size_t)qtok2 * 1024 + (2 * pr) * 64, o0, o1, h2);
;         store_o(ocat + (size_t)qtok2 * 1024 + (2 * pr + 1) * 64, u0, u1, h2);
.LBB0_343:
	v_mul_f32_e32 v63, v49, v0
	v_mul_f32_e32 v49, v0, v65
	v_mul_f32_e32 v0, v18, v18
	v_fmac_f32_e32 v0, v2, v2
	v_mul_f32_e32 v64, v19, v19
	v_fmac_f32_e32 v0, v66, v66
	v_fmac_f32_e32 v64, v3, v3
	v_fmac_f32_e32 v0, v34, v34
	v_fmac_f32_e32 v64, v67, v67
	v_add_f32_e32 v0, v147, v0
	v_fmac_f32_e32 v64, v35, v35
	v_add_f32_e32 v0, v64, v0
	v_mul_f32_e32 v64, v20, v20
	v_fmac_f32_e32 v64, v4, v4
	v_fmac_f32_e32 v64, v50, v50
	v_fmac_f32_e32 v64, v36, v36
	v_add_f32_e32 v0, v64, v0
	v_mul_f32_e32 v64, v21, v21
	v_fmac_f32_e32 v64, v5, v5
	v_fmac_f32_e32 v64, v51, v51
	v_fmac_f32_e32 v64, v37, v37
	v_add_f32_e32 v0, v64, v0
	v_pk_mul_f32 v[64:65], v[22:23], v[22:23]
	v_pk_mul_f32 v[68:69], v[24:25], v[24:25]
	v_pk_fma_f32 v[64:65], v[6:7], v[6:7], v[64:65]
	v_pk_fma_f32 v[68:69], v[8:9], v[8:9], v[68:69]
	v_pk_fma_f32 v[64:65], v[52:53], v[52:53], v[64:65]
	v_pk_mul_f32 v[70:71], v[26:27], v[26:27]
	v_pk_fma_f32 v[64:65], v[38:39], v[38:39], v[64:65]
	v_pk_fma_f32 v[68:69], v[54:55], v[54:55], v[68:69]
	v_add_f32_e32 v0, v64, v0
	v_pk_fma_f32 v[70:71], v[10:11], v[10:11], v[70:71]
	v_pk_fma_f32 v[68:69], v[40:41], v[40:41], v[68:69]
	v_add_f32_e32 v0, v65, v0
	v_pk_mul_f32 v[72:73], v[28:29], v[28:29]
	v_pk_fma_f32 v[70:71], v[56:57], v[56:57], v[70:71]
	v_add_f32_e32 v0, v68, v0
	v_pk_fma_f32 v[72:73], v[12:13], v[12:13], v[72:73]
	v_pk_fma_f32 v[70:71], v[42:43], v[42:43], v[70:71]
	v_add_f32_e32 v0, v69, v0
	v_pk_mul_f32 v[74:75], v[30:31], v[30:31]
	v_pk_fma_f32 v[72:73], v[58:59], v[58:59], v[72:73]
	v_add_f32_e32 v0, v70, v0
	v_pk_fma_f32 v[74:75], v[14:15], v[14:15], v[74:75]
	v_pk_fma_f32 v[72:73], v[44:45], v[44:45], v[72:73]
	v_add_f32_e32 v0, v71, v0
	v_pk_mul_f32 v[76:77], v[32:33], v[32:33]
	v_pk_fma_f32 v[74:75], v[60:61], v[60:61], v[74:75]
	v_add_f32_e32 v0, v72, v0
	v_pk_fma_f32 v[76:77], v[16:17], v[16:17], v[76:77]
	v_pk_fma_f32 v[74:75], v[46:47], v[46:47], v[74:75]
	v_add_f32_e32 v0, v73, v0
	v_add_f32_e32 v0, v74, v0
	v_pk_fma_f32 v[64:65], v[62:63], v[62:63], v[76:77]
	v_add_f32_e32 v0, v75, v0
	v_pk_fma_f32 v[64:65], v[48:49], v[48:49], v[64:65]
	s_lshl_b32 s34, s10, 8
	v_add_f32_e32 v0, v64, v0
	v_add_f32_e32 v147, v65, v0
	v_mov_b32_e32 v0, v228
	v_cvt_pk_bf16_f32 v2, v2, v3
	v_ashrrev_i32_e32 v64, 1, v0
	v_and_b32_e32 v64, 0xffffffe0, v64
	v_add_u32_e32 v64, s46, v64
	v_and_or_b32 v64, v0, 31, v64
	v_ashrrev_i32_e32 v65, 31, v64
	v_lshlrev_b64 v[64:65], 11, v[64:65]
	v_lshl_add_u64 v[64:65], s[66:67], 0, v[64:65]
	v_lshrrev_b32_e32 v0, 2, v0
	v_lshl_add_u64 v[68:69], v[64:65], 0, s[34:35]
	v_and_b32_e32 v0, 8, v0
	v_lshl_add_u64 v[68:69], v[68:69], 0, v[0:1]
	v_lshl_add_u64 v[68:69], v[68:69], 0, v[0:1]
	v_cvt_pk_bf16_f32 v18, v18, v19
	v_cvt_pk_bf16_f32 v19, v20, v21
	v_cvt_pk_bf16_f32 v20, v22, v23
	v_cvt_pk_bf16_f32 v21, v24, v25
	v_cvt_pk_bf16_f32 v26, v26, v27
	v_cvt_pk_bf16_f32 v27, v28, v29
	v_cvt_pk_bf16_f32 v28, v30, v31
	v_cvt_pk_bf16_f32 v29, v32, v33
	v_cvt_pk_bf16_f32 v3, v4, v5
	v_cvt_pk_bf16_f32 v4, v6, v7
	v_cvt_pk_bf16_f32 v5, v8, v9
	v_cvt_pk_bf16_f32 v10, v10, v11
	v_cvt_pk_bf16_f32 v11, v12, v13
	v_cvt_pk_bf16_f32 v12, v14, v15
	v_cvt_pk_bf16_f32 v13, v16, v17
	s_nop 1
	v_permlane32_swap_b32_e32 v18, v20
	v_permlane32_swap_b32_e32 v19, v21
	v_permlane32_swap_b32_e32 v26, v28
	v_permlane32_swap_b32_e32 v27, v29
	v_permlane32_swap_b32_e32 v2, v4
	v_permlane32_swap_b32_e32 v3, v5
	v_permlane32_swap_b32_e32 v10, v12
	v_permlane32_swap_b32_e32 v11, v13
	global_store_dwordx4 v[68:69], v[18:21], off
	global_store_dwordx4 v[68:69], v[26:29], off offset:32
	global_store_dwordx4 v[68:69], v[2:5], off offset:64
	global_store_dwordx4 v[68:69], v[10:13], off offset:96
	s_lshl_b32 s34, s49, 7
	v_lshl_add_u64 v[6:7], v[64:65], 0, s[34:35]
	v_lshl_add_u64 v[6:7], v[6:7], 0, v[0:1]
	v_lshl_add_u64 v[6:7], v[6:7], 0, v[0:1]
	v_cvt_pk_bf16_f32 v51, v50, v51
	v_cvt_pk_bf16_f32 v50, v66, v67
	v_cvt_pk_bf16_f32 v52, v52, v53
	v_cvt_pk_bf16_f32 v53, v54, v55
	v_cvt_pk_bf16_f32 v56, v56, v57
	v_cvt_pk_bf16_f32 v57, v58, v59
	v_cvt_pk_bf16_f32 v58, v60, v61
	v_cvt_pk_bf16_f32 v59, v62, v63
	v_cvt_pk_bf16_f32 v34, v34, v35
	v_cvt_pk_bf16_f32 v35, v36, v37
	v_cvt_pk_bf16_f32 v36, v38, v39
	v_cvt_pk_bf16_f32 v37, v40, v41
	v_cvt_pk_bf16_f32 v42, v42, v43
	v_cvt_pk_bf16_f32 v43, v44, v45
	v_cvt_pk_bf16_f32 v44, v46, v47
	v_cvt_pk_bf16_f32 v45, v48, v49
	s_nop 1
	v_permlane32_swap_b32_e32 v50, v52
	v_permlane32_swap_b32_e32 v51, v53
	v_permlane32_swap_b32_e32 v56, v58
	v_permlane32_swap_b32_e32 v57, v59
	v_permlane32_swap_b32_e32 v34, v36
	v_permlane32_swap_b32_e32 v35, v37
	v_permlane32_swap_b32_e32 v42, v44
	v_permlane32_swap_b32_e32 v43, v45
	global_store_dwordx4 v[6:7], v[50:53], off
	global_store_dwordx4 v[6:7], v[56:59], off offset:32
	global_store_dwordx4 v[6:7], v[34:37], off offset:64
	global_store_dwordx4 v[6:7], v[42:45], off offset:96
	s_xor_b64 s[0:1], s[38:39], -1
	s_mov_b64 s[38:39], 0
	s_and_b64 vcc, exec, s[0:1]
	s_nop 1
	s_cbranch_vccnz .LBB0_345
	s_mov_b32 s10, 1
	s_branch .LBB0_312

; DI float frsq(float x) { return __builtin_amdgcn_rsqf(x); }
; DI int crow(int i, int h) { return (i & 3) + 8 * (i >> 2) + 4 * h; }
; DI float xhalf(float v) { return __shfl_xor(v, 32); }
; DI void store_o(bf16_t* dst  , const f32x16& o0, const f32x16& o1, int h) {
; #pragma unroll
;   for (int g = 0; g < 4; ++g) {
;     uint2 u;
;     u.x = pk_bf16(o0[4 * g], o0[4 * g + 1]); u.y = pk_bf16(o0[4 * g + 2], o0[4 * g + 3]);
;     *(uint2*)(dst + 8 * g + 4 * h) = u;
;     u.x = pk_bf16(o1[4 * g], o1[4 * g + 1]); u.y = pk_bf16(o1[4 * g + 2], o1[4 * g + 3]);
;     *(uint2*)(dst + 32 + 8 * g + 4 * h) = u;
;   }
; }
; DI void phase_attn(const Params& p, int layer, char* smem) {
;     ...
;       float ssq = 0.f;
; #pragma unroll
;       for (int i = 0; i < 16; ++i) {
;         a0[i] -= lam * c0[i]; a1[i] -= lam * c1[i];
;         ssq += a0[i] * a0[i] + a1[i] * a1[i];
;       }
;       ssq += xhalf(ssq);
;       const float rstd = frsq(ssq * (1.f / 64.f) + EPS) * (1.f - li);
;       const float* gc = p.in[I_GC] + layer * 64;
; #pragma unroll
;       for (int i = 0; i < 16; ++i) {
;         a0[i] *= rstd * gc[crow(i, h)];
;         a1[i] *= rstd * gc[32 + crow(i, h)];
;       }
;       store_o(ocat + (size_t)qtok * 1024 + 512 + hd * 64, a0, a1, h);
.LBB0_406:
	v_readlane_b32 s0, v255, 10
	v_mul_f32_e32 v3, v0, v65
	v_lshlrev_b32_e32 v92, 4, v215
	v_readlane_b32 s1, v255, 11
	v_pk_fma_f32 v[52:53], v[150:151], v[52:53], v[24:25] op_sel_hi:[0,1,1] neg_lo:[1,0,0] neg_hi:[1,0,0]
	v_pk_fma_f32 v[32:33], v[150:151], v[2:3], v[32:33] op_sel_hi:[0,1,1] neg_lo:[1,0,0] neg_hi:[1,0,0]
	v_pk_fma_f32 v[46:47], v[150:151], v[56:57], v[26:27] op_sel_hi:[0,1,1] neg_lo:[1,0,0] neg_hi:[1,0,0]
	v_pk_mul_f32 v[58:59], v[52:53], v[52:53]
	v_pk_fma_f32 v[56:57], v[150:151], v[88:89], v[72:73] op_sel_hi:[0,1,1] neg_lo:[1,0,0] neg_hi:[1,0,0]
	global_load_dwordx4 v[2:5], v92, s[0:1] offset:224
	v_pk_fma_f32 v[54:55], v[150:151], v[54:55], v[22:23] op_sel_hi:[0,1,1] neg_lo:[1,0,0] neg_hi:[1,0,0]
	v_mul_f32_e32 v7, v49, v0
	v_pk_fma_f32 v[38:39], v[150:151], v[12:13], v[30:31] op_sel_hi:[0,1,1] neg_lo:[1,0,0] neg_hi:[1,0,0]
	v_pk_fma_f32 v[42:43], v[150:151], v[10:11], v[28:29] op_sel_hi:[0,1,1] neg_lo:[1,0,0] neg_hi:[1,0,0]
	v_pk_mul_f32 v[26:27], v[46:47], v[46:47]
	v_pk_fma_f32 v[48:49], v[150:151], v[90:91], v[74:75] op_sel_hi:[0,1,1] neg_lo:[1,0,0] neg_hi:[1,0,0]
	v_pk_fma_f32 v[72:73], v[56:57], v[56:57], v[58:59]
	v_pk_mul_f32 v[22:23], v[54:55], v[54:55]
	v_pk_fma_f32 v[58:59], v[150:151], v[86:87], v[70:71] op_sel_hi:[0,1,1] neg_lo:[1,0,0] neg_hi:[1,0,0]
	v_pk_fma_f32 v[36:37], v[150:151], v[6:7], v[80:81] op_sel_hi:[0,1,1] neg_lo:[1,0,0] neg_hi:[1,0,0]
	v_pk_mul_f32 v[16:17], v[32:33], v[32:33]
	v_pk_fma_f32 v[40:41], v[150:151], v[40:41], v[78:79] op_sel_hi:[0,1,1] neg_lo:[1,0,0] neg_hi:[1,0,0]
	v_pk_mul_f32 v[12:13], v[38:39], v[38:39]
	v_pk_fma_f32 v[44:45], v[150:151], v[14:15], v[76:77] op_sel_hi:[0,1,1] neg_lo:[1,0,0] neg_hi:[1,0,0]
	v_pk_mul_f32 v[28:29], v[42:43], v[42:43]
	v_pk_fma_f32 v[74:75], v[48:49], v[48:49], v[26:27]
	global_load_dwordx4 v[24:27], v92, s[0:1] offset:160
	v_pk_fma_f32 v[70:71], v[58:59], v[58:59], v[22:23]
	v_pk_fma_f32 v[50:51], v[150:151], v[50:51], v[20:21] op_sel_hi:[0,1,1] neg_lo:[1,0,0] neg_hi:[1,0,0]
	global_load_dwordx4 v[20:23], v92, s[0:1] offset:128
	global_load_dwordx4 v[6:9], v92, s[0:1] offset:96
	v_pk_fma_f32 v[60:61], v[36:37], v[36:37], v[16:17]
	v_pk_fma_f32 v[64:65], v[40:41], v[40:41], v[12:13]
	global_load_dwordx4 v[10:13], v92, s[0:1] offset:192
	global_load_dwordx4 v[14:17], v92, s[0:1] offset:64
	v_pk_fma_f32 v[76:77], v[44:45], v[44:45], v[28:29]
	global_load_dwordx4 v[28:31], v92, s[0:1] offset:32
	global_load_dwordx4 v[78:81], v92, s[0:1]
	v_pk_fma_f32 v[18:19], v[150:151], v[34:35], v[18:19] op_sel_hi:[0,1,1] neg_lo:[1,0,0] neg_hi:[1,0,0]
	v_pk_mul_f32 v[34:35], v[18:19], v[18:19]
	v_pk_fma_f32 v[66:67], v[150:151], v[82:83], v[66:67] op_sel_hi:[0,1,1] neg_lo:[1,0,0] neg_hi:[1,0,0]
	v_pk_mul_f32 v[86:87], v[50:51], v[50:51]
	v_pk_fma_f32 v[62:63], v[150:151], v[84:85], v[68:69] op_sel_hi:[0,1,1] neg_lo:[1,0,0] neg_hi:[1,0,0]
	v_pk_fma_f32 v[34:35], v[66:67], v[66:67], v[34:35]
	v_pk_fma_f32 v[68:69], v[62:63], v[62:63], v[86:87]
	v_add_f32_e32 v34, v34, v35
	v_add_f32_e32 v34, v68, v34
	v_add_f32_e32 v34, v69, v34
	v_add_f32_e32 v34, v70, v34
	v_add_f32_e32 v34, v71, v34
	v_add_f32_e32 v34, v72, v34
	v_add_f32_e32 v34, v73, v34
	v_add_f32_e32 v34, v74, v34
	v_add_f32_e32 v34, v75, v34
	v_add_f32_e32 v34, v76, v34
	v_add_f32_e32 v34, v77, v34
	v_add_f32_e32 v34, v64, v34
	v_add_f32_e32 v34, v65, v34
	v_add_f32_e32 v34, v60, v34
	v_add_f32_e32 v34, v61, v34
	ds_bpermute_b32 v35, v147, v34
	v_sub_f32_e32 v0, 1.0, v151
	s_lshl_b32 s34, s34, 7
	s_mov_b32 s8, s45
	s_waitcnt lgkmcnt(0)
	v_add_f32_e32 v34, v34, v35
	v_fmamk_f32 v34, v34, 0x3c800000, v229
	v_rsq_f32_e32 v34, v34
	s_nop 0
	v_mul_f32_e32 v0, v0, v34
	s_waitcnt vmcnt(7)
	v_pk_mul_f32 v[4:5], v[0:1], v[4:5] op_sel_hi:[0,1]
	v_pk_mul_f32 v[4:5], v[32:33], v[4:5]
	v_lshlrev_b64 v[32:33], 11, v[148:149]
	v_lshl_add_u64 v[32:33], s[66:67], 0, v[32:33]
	v_pk_mul_f32 v[2:3], v[0:1], v[2:3] op_sel_hi:[0,1]
	v_lshl_add_u64 v[32:33], v[32:33], 0, s[34:35]
	v_pk_mul_f32 v[2:3], v[38:39], v[2:3]
	s_waitcnt vmcnt(6)
	v_pk_mul_f32 v[24:25], v[24:25], v[0:1] op_sel_hi:[1,0]
	v_pk_mul_f32 v[26:27], v[26:27], v[0:1] op_sel_hi:[1,0]
	v_pk_mul_f32 v[24:25], v[54:55], v[24:25]
	s_waitcnt vmcnt(5)
	v_pk_mul_f32 v[20:21], v[20:21], v[0:1] op_sel_hi:[1,0]
	v_pk_mul_f32 v[22:23], v[22:23], v[0:1] op_sel_hi:[1,0]
	v_pk_mul_f32 v[18:19], v[18:19], v[20:21]
	v_pk_mul_f32 v[22:23], v[50:51], v[22:23]
	s_waitcnt vmcnt(3)
	v_pk_mul_f32 v[10:11], v[10:11], v[0:1] op_sel_hi:[1,0]
	s_waitcnt vmcnt(2)
	v_pk_mul_f32 v[14:15], v[14:15], v[0:1] op_sel_hi:[1,0]
	v_pk_mul_f32 v[16:17], v[16:17], v[0:1] op_sel_hi:[1,0]
	s_waitcnt vmcnt(1)
	v_pk_mul_f32 v[28:29], v[28:29], v[0:1] op_sel_hi:[1,0]
	s_waitcnt vmcnt(0)
	v_pk_mul_f32 v[34:35], v[78:79], v[0:1] op_sel_hi:[1,0]
	v_pk_mul_f32 v[20:21], v[80:81], v[0:1] op_sel_hi:[1,0]
	v_pk_mul_f32 v[30:31], v[30:31], v[0:1] op_sel_hi:[1,0]
	v_pk_mul_f32 v[12:13], v[12:13], v[0:1] op_sel_hi:[1,0]
	v_pk_mul_f32 v[6:7], v[0:1], v[6:7] op_sel_hi:[0,1]
	v_pk_mul_f32 v[8:9], v[0:1], v[8:9] op_sel_hi:[0,1]
	v_lshlrev_b32_e32 v0, 3, v215
	v_pk_mul_f32 v[28:29], v[58:59], v[28:29]
	v_pk_mul_f32 v[30:31], v[56:57], v[30:31]
	v_lshl_add_u64 v[32:33], v[32:33], 0, v[0:1]
	v_pk_mul_f32 v[34:35], v[66:67], v[34:35]
	v_pk_mul_f32 v[20:21], v[62:63], v[20:21]
	v_pk_mul_f32 v[26:27], v[52:53], v[26:27]
	v_pk_mul_f32 v[14:15], v[48:49], v[14:15]
	v_pk_mul_f32 v[10:11], v[46:47], v[10:11]
	v_pk_mul_f32 v[16:17], v[44:45], v[16:17]
	v_pk_mul_f32 v[12:13], v[42:43], v[12:13]
	v_pk_mul_f32 v[6:7], v[40:41], v[6:7]
	v_pk_mul_f32 v[8:9], v[36:37], v[8:9]
	v_lshl_add_u64 v[32:33], v[32:33], 0, v[0:1]
	v_cvt_pk_bf16_f32 v34, v34, v35
	v_cvt_pk_bf16_f32 v35, v20, v21
	v_cvt_pk_bf16_f32 v36, v28, v29
	v_cvt_pk_bf16_f32 v37, v30, v31
	v_cvt_pk_bf16_f32 v18, v18, v19
	v_cvt_pk_bf16_f32 v19, v22, v23
	v_cvt_pk_bf16_f32 v20, v24, v25
	v_cvt_pk_bf16_f32 v21, v26, v27
	v_cvt_pk_bf16_f32 v14, v14, v15
	v_cvt_pk_bf16_f32 v15, v16, v17
	v_cvt_pk_bf16_f32 v16, v6, v7
	v_cvt_pk_bf16_f32 v17, v8, v9
	v_cvt_pk_bf16_f32 v10, v10, v11
	v_cvt_pk_bf16_f32 v11, v12, v13
	v_cvt_pk_bf16_f32 v12, v2, v3
	v_cvt_pk_bf16_f32 v13, v4, v5
	s_nop 1
	v_permlane32_swap_b32_e32 v34, v36
	v_permlane32_swap_b32_e32 v35, v37
	v_permlane32_swap_b32_e32 v18, v20
	v_permlane32_swap_b32_e32 v19, v21
	v_permlane32_swap_b32_e32 v14, v16
	v_permlane32_swap_b32_e32 v15, v17
	v_permlane32_swap_b32_e32 v10, v12
	v_permlane32_swap_b32_e32 v11, v13
	global_store_dwordx4 v[32:33], v[34:37], off offset:1024
	global_store_dwordx4 v[32:33], v[14:17], off offset:1056
	global_store_dwordx4 v[32:33], v[18:21], off offset:1088
	global_store_dwordx4 v[32:33], v[10:13], off offset:1120
	s_nop 1
	s_cbranch_execz .LBB0_311
	s_branch .LBB0_346
